# P8 final-norm row loop rewritten: whole next row prefetched into a second register buffer, gamma loaded once per wave (was 2 KB in flight per wave)
# speedup vs baseline: 1.0132x; 1.0020x over previous
; #define GAS __attribute__((address_space(1)))
; __global__ void __launch_bounds__(NWAVES * 64, 2) mega(Args args) {
;     ...
;     if (IN(8)) {
;         const float* rss = (const float*)(ws + WS_RSS2); const GAS f32x4* gr = (const GAS f32x4*)args.in[16] + F.lane;
;         for (int m = gw; m < M; m += NGW) { const float rstd = 1.f / sqrtf(rss[m] * (1.f / D) + EPS); GAS f32x4* o = (GAS f32x4*)(args.out + (size_t)m * D) + F.lane;
; #pragma unroll
;             for (int j = 0; j < 8; ++j) { const f32x4 gg = gr[64 * j]; f32x4 v = o[64 * j]; v = v * rstd; v.x *= gg.x; v.y *= gg.y; v.z *= gg.z; v.w *= gg.w; o[64 * j] = v; } }
.LBB0_974:
	s_cmp_lt_i32 s90, 9
	s_cselect_b64 s[2:3], -1, 0
	s_and_b64 s[0:1], s[2:3], s[0:1]
	s_andn2_b64 vcc, exec, s[0:1]
	s_cbranch_vccnz .LBB0_978
	s_cmpk_gt_i32 s74, 0x3fff
	s_cbranch_scc1 .LBB0_978
	v_lshlrev_b32_e32 v0, 4, v156
	v_mov_b32_e32 v1, 0
	v_mov_b32_e32 v96, 0x358637bd
	v_mov_b32_e32 v97, 0x260
	s_mov_b32 s22, 0xf800000
	s_add_u32 s10, s84, 0x1000
	s_addc_u32 s11, s85, 0
	global_load_dwordx4 v[32:35], v0, s[84:85]
	global_load_dwordx4 v[36:39], v0, s[84:85] offset:1024
	global_load_dwordx4 v[40:43], v0, s[84:85] offset:2048
	global_load_dwordx4 v[44:47], v0, s[84:85] offset:3072
	global_load_dwordx4 v[48:51], v0, s[10:11]
	global_load_dwordx4 v[52:55], v0, s[10:11] offset:1024
	global_load_dwordx4 v[56:59], v0, s[10:11] offset:2048
	global_load_dwordx4 v[60:63], v0, s[10:11] offset:3072
	s_ashr_i32 s75, s74, 31
	s_lshl_b64 s[2:3], s[74:75], 2
	s_add_u32 s2, s88, s2
	s_addc_u32 s3, s89, s3
	s_add_u32 s2, s2, 0x110000
	s_addc_u32 s3, s3, 0
	s_lshl_b64 s[6:7], s[74:75], 13
	s_add_u32 s6, s86, s6
	s_addc_u32 s7, s87, s7
	s_add_u32 s12, s6, 0x1000
	s_addc_u32 s13, s7, 0
	s_ashr_i32 s79, s78, 31
	s_lshl_b64 s[4:5], s[78:79], 2
	s_lshl_b64 s[8:9], s[78:79], 13
	global_load_dword v192, v1, s[2:3]
	global_load_dwordx4 v[128:131], v0, s[6:7]
	global_load_dwordx4 v[132:135], v0, s[6:7] offset:1024
	global_load_dwordx4 v[136:139], v0, s[6:7] offset:2048
	global_load_dwordx4 v[140:143], v0, s[6:7] offset:3072
	global_load_dwordx4 v[144:147], v0, s[12:13]
	global_load_dwordx4 v[148:151], v0, s[12:13] offset:1024
	global_load_dwordx4 v[152:155], v0, s[12:13] offset:2048
	global_load_dwordx4 v[156:159], v0, s[12:13] offset:3072
.Lp8_loop_0:
	s_add_i32 s74, s74, s78
	s_cmpk_lt_i32 s74, 0x4000
	s_cbranch_scc0 .Lp8_last_0
	s_add_u32 s2, s2, s4
	s_addc_u32 s3, s3, s5
	s_add_u32 s16, s6, s8
	s_addc_u32 s17, s7, s9
	s_add_u32 s18, s16, 0x1000
	s_addc_u32 s19, s17, 0
	global_load_dword v193, v1, s[2:3]
	global_load_dwordx4 v[160:163], v0, s[16:17]
	global_load_dwordx4 v[164:167], v0, s[16:17] offset:1024
	global_load_dwordx4 v[168:171], v0, s[16:17] offset:2048
	global_load_dwordx4 v[172:175], v0, s[16:17] offset:3072
	global_load_dwordx4 v[176:179], v0, s[18:19]
	global_load_dwordx4 v[180:183], v0, s[18:19] offset:1024
	global_load_dwordx4 v[184:187], v0, s[18:19] offset:2048
	global_load_dwordx4 v[188:191], v0, s[18:19] offset:3072
	s_mov_b32 s20, 0
	s_waitcnt vmcnt(9)
	s_branch .Lp8_proc_0
.Lp8_last_0:
	s_mov_b32 s20, 1
	s_waitcnt vmcnt(0)
.Lp8_proc_0:
	v_fmamk_f32 v100, v192, 0x3a000000, v96
	v_mul_f32_e32 v101, 0x4f800000, v100
	v_cmp_gt_f32_e32 vcc, s22, v100
	s_nop 1
	v_cndmask_b32_e32 v100, v100, v101, vcc
	v_sqrt_f32_e32 v101, v100
	s_nop 0
	v_add_u32_e32 v102, -1, v101
	v_add_u32_e32 v103, 1, v101
	v_fma_f32 v104, -v102, v101, v100
	v_fma_f32 v105, -v103, v101, v100
	v_cmp_ge_f32_e64 s[0:1], 0, v104
	s_nop 1
	v_cndmask_b32_e64 v101, v101, v102, s[0:1]
	v_cmp_lt_f32_e64 s[0:1], 0, v105
	s_nop 1
	v_cndmask_b32_e64 v101, v101, v103, s[0:1]
	v_mul_f32_e32 v102, 0x37800000, v101
	v_cndmask_b32_e32 v101, v101, v102, vcc
	v_cmp_class_f32_e32 vcc, v100, v97
	s_nop 1
	v_cndmask_b32_e32 v100, v101, v100, vcc
	v_div_scale_f32 v101, s[0:1], v100, v100, 1.0
	v_rcp_f32_e32 v103, v101
	v_div_scale_f32 v102, vcc, 1.0, v100, 1.0
	v_fma_f32 v104, -v101, v103, 1.0
	v_fmac_f32_e32 v103, v104, v103
	v_mul_f32_e32 v104, v102, v103
	v_fma_f32 v105, -v101, v104, v102
	v_fmac_f32_e32 v104, v105, v103
	v_fma_f32 v101, -v101, v104, v102
	v_div_fmas_f32 v101, v101, v103, v104
	v_div_fixup_f32 v98, v101, v100, 1.0
	v_pk_mul_f32 v[128:129], v[98:99], v[128:129] op_sel_hi:[0,1]
	v_pk_mul_f32 v[130:131], v[98:99], v[130:131] op_sel_hi:[0,1]
	v_pk_mul_f32 v[128:129], v[32:33], v[128:129]
	v_pk_mul_f32 v[130:131], v[34:35], v[130:131]
	global_store_dwordx4 v0, v[128:131], s[6:7]
	v_pk_mul_f32 v[132:133], v[98:99], v[132:133] op_sel_hi:[0,1]
	v_pk_mul_f32 v[134:135], v[98:99], v[134:135] op_sel_hi:[0,1]
	v_pk_mul_f32 v[132:133], v[36:37], v[132:133]
	v_pk_mul_f32 v[134:135], v[38:39], v[134:135]
	global_store_dwordx4 v0, v[132:135], s[6:7] offset:1024
	v_pk_mul_f32 v[136:137], v[98:99], v[136:137] op_sel_hi:[0,1]
	v_pk_mul_f32 v[138:139], v[98:99], v[138:139] op_sel_hi:[0,1]
	v_pk_mul_f32 v[136:137], v[40:41], v[136:137]
	v_pk_mul_f32 v[138:139], v[42:43], v[138:139]
	global_store_dwordx4 v0, v[136:139], s[6:7] offset:2048
	v_pk_mul_f32 v[140:141], v[98:99], v[140:141] op_sel_hi:[0,1]
	v_pk_mul_f32 v[142:143], v[98:99], v[142:143] op_sel_hi:[0,1]
	v_pk_mul_f32 v[140:141], v[44:45], v[140:141]
	v_pk_mul_f32 v[142:143], v[46:47], v[142:143]
	global_store_dwordx4 v0, v[140:143], s[6:7] offset:3072
	v_pk_mul_f32 v[144:145], v[98:99], v[144:145] op_sel_hi:[0,1]
	v_pk_mul_f32 v[146:147], v[98:99], v[146:147] op_sel_hi:[0,1]
	v_pk_mul_f32 v[144:145], v[48:49], v[144:145]
	v_pk_mul_f32 v[146:147], v[50:51], v[146:147]
	global_store_dwordx4 v0, v[144:147], s[12:13]
	v_pk_mul_f32 v[148:149], v[98:99], v[148:149] op_sel_hi:[0,1]
	v_pk_mul_f32 v[150:151], v[98:99], v[150:151] op_sel_hi:[0,1]
	v_pk_mul_f32 v[148:149], v[52:53], v[148:149]
	v_pk_mul_f32 v[150:151], v[54:55], v[150:151]
	global_store_dwordx4 v0, v[148:151], s[12:13] offset:1024
	v_pk_mul_f32 v[152:153], v[98:99], v[152:153] op_sel_hi:[0,1]
	v_pk_mul_f32 v[154:155], v[98:99], v[154:155] op_sel_hi:[0,1]
	v_pk_mul_f32 v[152:153], v[56:57], v[152:153]
	v_pk_mul_f32 v[154:155], v[58:59], v[154:155]
	global_store_dwordx4 v0, v[152:155], s[12:13] offset:2048
	v_pk_mul_f32 v[156:157], v[98:99], v[156:157] op_sel_hi:[0,1]
	v_pk_mul_f32 v[158:159], v[98:99], v[158:159] op_sel_hi:[0,1]
	v_pk_mul_f32 v[156:157], v[60:61], v[156:157]
	v_pk_mul_f32 v[158:159], v[62:63], v[158:159]
	global_store_dwordx4 v0, v[156:159], s[12:13] offset:3072
	s_cmp_eq_u32 s20, 1
	s_cbranch_scc1 .LBB0_978
	s_mov_b64 s[6:7], s[16:17]
	s_mov_b64 s[12:13], s[18:19]
	s_branch .Lp8_loop_1
.Lp8_loop_1:
	s_add_i32 s74, s74, s78
	s_cmpk_lt_i32 s74, 0x4000
	s_cbranch_scc0 .Lp8_last_1
	s_add_u32 s2, s2, s4
	s_addc_u32 s3, s3, s5
	s_add_u32 s16, s6, s8
	s_addc_u32 s17, s7, s9
	s_add_u32 s18, s16, 0x1000
	s_addc_u32 s19, s17, 0
	global_load_dword v192, v1, s[2:3]
	global_load_dwordx4 v[128:131], v0, s[16:17]
	global_load_dwordx4 v[132:135], v0, s[16:17] offset:1024
	global_load_dwordx4 v[136:139], v0, s[16:17] offset:2048
	global_load_dwordx4 v[140:143], v0, s[16:17] offset:3072
	global_load_dwordx4 v[144:147], v0, s[18:19]
	global_load_dwordx4 v[148:151], v0, s[18:19] offset:1024
	global_load_dwordx4 v[152:155], v0, s[18:19] offset:2048
	global_load_dwordx4 v[156:159], v0, s[18:19] offset:3072
	s_mov_b32 s20, 0
	s_waitcnt vmcnt(9)
	s_branch .Lp8_proc_1

; #define GAS __attribute__((address_space(1)))
; __global__ void __launch_bounds__(NWAVES * 64, 2) mega(Args args) {
;     ...
;         for (int m = gw; m < M; m += NGW) { const float rstd = 1.f / sqrtf(rss[m] * (1.f / D) + EPS); GAS f32x4* o = (GAS f32x4*)(args.out + (size_t)m * D) + F.lane;
; #pragma unroll
;             for (int j = 0; j < 8; ++j) { const f32x4 gg = gr[64 * j]; f32x4 v = o[64 * j]; v = v * rstd; v.x *= gg.x; v.y *= gg.y; v.z *= gg.z; v.w *= gg.w; o[64 * j] = v; } }
.Lp8_proc_1:
	v_fmamk_f32 v100, v193, 0x3a000000, v96
	v_mul_f32_e32 v101, 0x4f800000, v100
	v_cmp_gt_f32_e32 vcc, s22, v100
	s_nop 1
	v_cndmask_b32_e32 v100, v100, v101, vcc
	v_sqrt_f32_e32 v101, v100
	s_nop 0
	v_add_u32_e32 v102, -1, v101
	v_add_u32_e32 v103, 1, v101
	v_fma_f32 v104, -v102, v101, v100
	v_fma_f32 v105, -v103, v101, v100
	v_cmp_ge_f32_e64 s[0:1], 0, v104
	s_nop 1
	v_cndmask_b32_e64 v101, v101, v102, s[0:1]
	v_cmp_lt_f32_e64 s[0:1], 0, v105
	s_nop 1
	v_cndmask_b32_e64 v101, v101, v103, s[0:1]
	v_mul_f32_e32 v102, 0x37800000, v101
	v_cndmask_b32_e32 v101, v101, v102, vcc
	v_cmp_class_f32_e32 vcc, v100, v97
	s_nop 1
	v_cndmask_b32_e32 v100, v101, v100, vcc
	v_div_scale_f32 v101, s[0:1], v100, v100, 1.0
	v_rcp_f32_e32 v103, v101
	v_div_scale_f32 v102, vcc, 1.0, v100, 1.0
	v_fma_f32 v104, -v101, v103, 1.0
	v_fmac_f32_e32 v103, v104, v103
	v_mul_f32_e32 v104, v102, v103
	v_fma_f32 v105, -v101, v104, v102
	v_fmac_f32_e32 v104, v105, v103
	v_fma_f32 v101, -v101, v104, v102
	v_div_fmas_f32 v101, v101, v103, v104
	v_div_fixup_f32 v98, v101, v100, 1.0
	v_pk_mul_f32 v[160:161], v[98:99], v[160:161] op_sel_hi:[0,1]
	v_pk_mul_f32 v[162:163], v[98:99], v[162:163] op_sel_hi:[0,1]
	v_pk_mul_f32 v[160:161], v[32:33], v[160:161]
	v_pk_mul_f32 v[162:163], v[34:35], v[162:163]
	global_store_dwordx4 v0, v[160:163], s[6:7]
	v_pk_mul_f32 v[164:165], v[98:99], v[164:165] op_sel_hi:[0,1]
	v_pk_mul_f32 v[166:167], v[98:99], v[166:167] op_sel_hi:[0,1]
	v_pk_mul_f32 v[164:165], v[36:37], v[164:165]
	v_pk_mul_f32 v[166:167], v[38:39], v[166:167]
	global_store_dwordx4 v0, v[164:167], s[6:7] offset:1024
	v_pk_mul_f32 v[168:169], v[98:99], v[168:169] op_sel_hi:[0,1]
	v_pk_mul_f32 v[170:171], v[98:99], v[170:171] op_sel_hi:[0,1]
	v_pk_mul_f32 v[168:169], v[40:41], v[168:169]
	v_pk_mul_f32 v[170:171], v[42:43], v[170:171]
	global_store_dwordx4 v0, v[168:171], s[6:7] offset:2048
	v_pk_mul_f32 v[172:173], v[98:99], v[172:173] op_sel_hi:[0,1]
	v_pk_mul_f32 v[174:175], v[98:99], v[174:175] op_sel_hi:[0,1]
	v_pk_mul_f32 v[172:173], v[44:45], v[172:173]
	v_pk_mul_f32 v[174:175], v[46:47], v[174:175]
	global_store_dwordx4 v0, v[172:175], s[6:7] offset:3072
	v_pk_mul_f32 v[176:177], v[98:99], v[176:177] op_sel_hi:[0,1]
	v_pk_mul_f32 v[178:179], v[98:99], v[178:179] op_sel_hi:[0,1]
	v_pk_mul_f32 v[176:177], v[48:49], v[176:177]
	v_pk_mul_f32 v[178:179], v[50:51], v[178:179]
	global_store_dwordx4 v0, v[176:179], s[12:13]
	v_pk_mul_f32 v[180:181], v[98:99], v[180:181] op_sel_hi:[0,1]
	v_pk_mul_f32 v[182:183], v[98:99], v[182:183] op_sel_hi:[0,1]
	v_pk_mul_f32 v[180:181], v[52:53], v[180:181]
	v_pk_mul_f32 v[182:183], v[54:55], v[182:183]
	global_store_dwordx4 v0, v[180:183], s[12:13] offset:1024
	v_pk_mul_f32 v[184:185], v[98:99], v[184:185] op_sel_hi:[0,1]
	v_pk_mul_f32 v[186:187], v[98:99], v[186:187] op_sel_hi:[0,1]
	v_pk_mul_f32 v[184:185], v[56:57], v[184:185]
	v_pk_mul_f32 v[186:187], v[58:59], v[186:187]
	global_store_dwordx4 v0, v[184:187], s[12:13] offset:2048
	v_pk_mul_f32 v[188:189], v[98:99], v[188:189] op_sel_hi:[0,1]
	v_pk_mul_f32 v[190:191], v[98:99], v[190:191] op_sel_hi:[0,1]
	v_pk_mul_f32 v[188:189], v[60:61], v[188:189]
	v_pk_mul_f32 v[190:191], v[62:63], v[190:191]
	global_store_dwordx4 v0, v[188:191], s[12:13] offset:3072
	s_cmp_eq_u32 s20, 1
	s_cbranch_scc1 .LBB0_978
	s_mov_b64 s[6:7], s[16:17]
	s_mov_b64 s[12:13], s[18:19]
	s_branch .Lp8_loop_0
